# P7 hand-offs: one L2 write-back and one count of 8 per publishing workgroup (after the GEMM's closing barrier) instead of one per wave
# speedup vs baseline: 1.0430x; 1.0111x over previous
; #define PG8_STAGE(bufoff, gbase, voff) do { _Pragma("unroll") for (int _i = 0; _i < 2; ++_i) \
;         __builtin_amdgcn_global_load_lds((const unsigned*)((const char*)(gbase) + (voff)[_i]), (LAS unsigned*)(lds + (bufoff) + ldsw + _i * 8192), 16, 0, 0); } while (0)
; #define PG8_LDA(dst, b, h) do { _Pragma("unroll") for (int m = 0; m < 4; ++m) _Pragma("unroll") for (int k = 0; k < 2; ++k) dst[m][k] = *(const LAS bf16x8*)(lds + PG8_SA(b, h) + aoff + m * 2048 + k * 1024); } while (0)
; #define PG8_LDB(dst, b, h) do { _Pragma("unroll") for (int n = 0; n < 2; ++n) _Pragma("unroll") for (int k = 0; k < 2; ++k) dst[n][k] = *(const LAS bf16x8*)(lds + PG8_SB(b, h) + boff + n * 2048 + k * 1024); } while (0)
; #define PG8_WAIT_V(n) asm volatile("s_waitcnt vmcnt(" #n ")" ::: "memory")
; #define PG8_WAIT_L(n) asm volatile("s_waitcnt lgkmcnt(" #n ")" ::: "memory")
; #define PG8_BAR __builtin_amdgcn_s_barrier()
; #define PG8_SCHED __builtin_amdgcn_sched_barrier(0)
; template <class Epi, class S_t>
; __device__ __forceinline__ void gemm_phase(LAS unsigned char* lds, int lda, int ldb, const S_t& S, const Epi& E) {
;     ...
;             PG8_LDB(B0, 0, 0); PG8_SCHED; PG8_LDA(At, 0, 0); PG8_STAGE(PG8_SA(1, 1), a1 + hstepA, voffA);
;             PG8_WAIT_L(8); PG8_BAR; PG8_WAIT_L(0); PG8_MMA(0, 0, At, B0); PG8_BAR; PG8_SCHED;
;             PG8_LDB(B1, 0, 1); PG8_STAGE(PG8_SB(0, 0), b2, voffB);
;             PG8_BAR; PG8_WAIT_L(0); PG8_MMA(0, 1, At, B1); PG8_BAR;
;             PG8_LDA(At, 0, 1); PG8_STAGE(PG8_SA(0, 0), a2, voffA);
;             PG8_BAR; PG8_WAIT_L(0); PG8_MMA(1, 0, At, B0); PG8_BAR; PG8_SCHED;
;             PG8_STAGE(PG8_SB(0, 1), b2 + hstepB, voffB);
;             PG8_WAIT_V(6); PG8_BAR; PG8_MMA(1, 1, At, B1); PG8_BAR;
;             PG8_LDB(B0, 1, 0); PG8_SCHED; PG8_LDA(At, 1, 0); PG8_STAGE(PG8_SA(0, 1), a2 + hstepA, voffA);
;             PG8_WAIT_L(8); PG8_BAR; PG8_WAIT_L(0); PG8_MMA(0, 0, At, B0); PG8_BAR; PG8_SCHED;
;             PG8_LDB(B1, 1, 1); PG8_STAGE(PG8_SB(1, 0), b3, voffB);
;             PG8_BAR; PG8_WAIT_L(0); PG8_MMA(0, 1, At, B1); PG8_BAR;
;             PG8_LDA(At, 1, 1); PG8_STAGE(PG8_SA(1, 0), a3, voffA);
;             PG8_BAR; PG8_WAIT_L(0); PG8_MMA(1, 0, At, B0); PG8_BAR; PG8_SCHED;
;             PG8_STAGE(PG8_SB(1, 1), b3 + hstepB, voffB);
;             PG8_WAIT_V(6); PG8_BAR; PG8_MMA(1, 1, At, B1); PG8_BAR;
.LBB0_945:
	ds_read_b128 v[140:143], v149
	ds_read_b128 v[152:155], v149 offset:1024
	ds_read_b128 v[156:159], v149 offset:2048
	ds_read_b128 v[160:163], v149 offset:3072
	s_add_u32 s33, s60, 0xfffc0080
	s_addc_u32 s52, s61, -1
	s_cmp_eq_u32 s43, 12
	s_cselect_b32 s67, s59, s52
	s_cselect_b32 s66, s58, s33
	s_cselect_b32 s63, s57, s1
	s_cselect_b32 s62, s56, s0
	s_add_i32 m0, s16, 0xc000
	ds_read_b128 v[164:167], v150
	ds_read_b128 v[168:171], v150 offset:1024
	ds_read_b128 v[172:175], v150 offset:2048
	ds_read_b128 v[176:179], v150 offset:3072
	ds_read_b128 v[180:183], v150 offset:4096
	ds_read_b128 v[186:189], v150 offset:5120
	ds_read_b128 v[190:193], v150 offset:6144
	ds_read_b128 v[194:197], v150 offset:7168
	global_load_lds_dwordx4 v136, s[60:61]
	s_add_i32 m0, s16, 0xe000
	s_nop 0
	global_load_lds_dwordx4 v138, s[60:61]
	s_waitcnt lgkmcnt(8)
	s_barrier
	s_waitcnt lgkmcnt(0)
	s_setprio 1
	s_waitcnt lgkmcnt(0)
	v_mfma_f32_16x16x32_bf16 v[124:127], v[140:143], v[164:167], v[124:127]
	v_mfma_f32_16x16x32_bf16 v[120:123], v[156:159], v[164:167], v[120:123]
	v_mfma_f32_16x16x32_bf16 v[116:119], v[140:143], v[172:175], v[116:119]
	v_mfma_f32_16x16x32_bf16 v[108:111], v[156:159], v[172:175], v[108:111]
	v_mfma_f32_16x16x32_bf16 v[96:99], v[140:143], v[180:183], v[96:99]
	v_mfma_f32_16x16x32_bf16 v[88:91], v[156:159], v[180:183], v[88:91]
	v_mfma_f32_16x16x32_bf16 v[80:83], v[140:143], v[190:193], v[80:83]
	v_mfma_f32_16x16x32_bf16 v[72:75], v[156:159], v[190:193], v[72:75]
	v_mfma_f32_16x16x32_bf16 v[124:127], v[152:155], v[168:171], v[124:127]
	v_mfma_f32_16x16x32_bf16 v[120:123], v[160:163], v[168:171], v[120:123]
	v_mfma_f32_16x16x32_bf16 v[116:119], v[152:155], v[176:179], v[116:119]
	v_mfma_f32_16x16x32_bf16 v[108:111], v[160:163], v[176:179], v[108:111]
	v_mfma_f32_16x16x32_bf16 v[96:99], v[152:155], v[186:189], v[96:99]
	v_mfma_f32_16x16x32_bf16 v[88:91], v[160:163], v[186:189], v[88:91]
	v_mfma_f32_16x16x32_bf16 v[80:83], v[152:155], v[194:197], v[80:83]
	v_mfma_f32_16x16x32_bf16 v[72:75], v[160:163], v[194:197], v[72:75]
	s_setprio 0
	s_barrier
	s_add_i32 s33, s88, s5
	s_add_u32 s98, s62, s10
	s_addc_u32 s99, s63, s11
	s_mov_b32 m0, s33
	ds_read_b128 v[198:201], v151
	ds_read_b128 v[202:205], v151 offset:1024
	ds_read_b128 v[206:209], v151 offset:2048
	ds_read_b128 v[222:225], v151 offset:3072
	global_load_lds_dwordx4 v130, s[62:63]
	s_add_i32 m0, s33, 0x2000
	s_nop 0
	global_load_lds_dwordx4 v134, s[62:63]
	s_barrier
	s_waitcnt lgkmcnt(0)
	s_setprio 1
	s_waitcnt lgkmcnt(0)
	v_mfma_f32_16x16x32_bf16 v[112:115], v[198:201], v[164:167], v[112:115]
	v_mfma_f32_16x16x32_bf16 v[104:107], v[206:209], v[164:167], v[104:107]
	v_mfma_f32_16x16x32_bf16 v[100:103], v[198:201], v[172:175], v[100:103]
	v_mfma_f32_16x16x32_bf16 v[92:95], v[206:209], v[172:175], v[92:95]
	v_mfma_f32_16x16x32_bf16 v[84:87], v[198:201], v[180:183], v[84:87]
	v_mfma_f32_16x16x32_bf16 v[76:79], v[206:209], v[180:183], v[76:79]
	v_mfma_f32_16x16x32_bf16 v[68:71], v[198:201], v[190:193], v[68:71]
	v_mfma_f32_16x16x32_bf16 v[64:67], v[206:209], v[190:193], v[64:67]
	v_mfma_f32_16x16x32_bf16 v[112:115], v[202:205], v[168:171], v[112:115]
	v_mfma_f32_16x16x32_bf16 v[104:107], v[222:225], v[168:171], v[104:107]
	v_mfma_f32_16x16x32_bf16 v[100:103], v[202:205], v[176:179], v[100:103]
	v_mfma_f32_16x16x32_bf16 v[92:95], v[222:225], v[176:179], v[92:95]
	v_mfma_f32_16x16x32_bf16 v[84:87], v[202:205], v[186:189], v[84:87]
	v_mfma_f32_16x16x32_bf16 v[76:79], v[222:225], v[186:189], v[76:79]
	v_mfma_f32_16x16x32_bf16 v[68:71], v[202:205], v[194:197], v[68:71]
	v_mfma_f32_16x16x32_bf16 v[64:67], v[222:225], v[194:197], v[64:67]
	s_setprio 0
	s_mov_b32 m0, s16
	s_add_u32 s100, s66, s10
	s_addc_u32 s101, s67, s11
	s_barrier
	ds_read_b128 v[164:167], v150 offset:16384
	ds_read_b128 v[168:171], v150 offset:17408
	ds_read_b128 v[172:175], v150 offset:18432
	ds_read_b128 v[176:179], v150 offset:19456
	ds_read_b128 v[180:183], v150 offset:20480
	ds_read_b128 v[186:189], v150 offset:21504
	ds_read_b128 v[190:193], v150 offset:22528
	ds_read_b128 v[194:197], v150 offset:23552
	global_load_lds_dwordx4 v128, s[66:67]
	s_mov_b32 m0, s17
	s_nop 0
	global_load_lds_dwordx4 v132, s[66:67]
	s_barrier
	s_waitcnt lgkmcnt(0)
	s_setprio 1
	s_waitcnt lgkmcnt(0)
	v_mfma_f32_16x16x32_bf16 v[60:63], v[140:143], v[164:167], v[60:63]
	v_mfma_f32_16x16x32_bf16 v[56:59], v[156:159], v[164:167], v[56:59]
	v_mfma_f32_16x16x32_bf16 v[48:51], v[140:143], v[172:175], v[48:51]
	v_mfma_f32_16x16x32_bf16 v[40:43], v[156:159], v[172:175], v[40:43]
	v_mfma_f32_16x16x32_bf16 v[32:35], v[140:143], v[180:183], v[32:35]
	v_mfma_f32_16x16x32_bf16 v[24:27], v[156:159], v[180:183], v[24:27]
	v_mfma_f32_16x16x32_bf16 v[16:19], v[140:143], v[190:193], v[16:19]
	v_mfma_f32_16x16x32_bf16 v[8:11], v[156:159], v[190:193], v[8:11]
	v_mfma_f32_16x16x32_bf16 v[60:63], v[152:155], v[168:171], v[60:63]
	v_mfma_f32_16x16x32_bf16 v[56:59], v[160:163], v[168:171], v[56:59]
	v_mfma_f32_16x16x32_bf16 v[48:51], v[152:155], v[176:179], v[48:51]
	v_mfma_f32_16x16x32_bf16 v[40:43], v[160:163], v[176:179], v[40:43]
	v_mfma_f32_16x16x32_bf16 v[32:35], v[152:155], v[186:189], v[32:35]
	v_mfma_f32_16x16x32_bf16 v[24:27], v[160:163], v[186:189], v[24:27]
	v_mfma_f32_16x16x32_bf16 v[16:19], v[152:155], v[194:197], v[16:19]
	v_mfma_f32_16x16x32_bf16 v[8:11], v[160:163], v[194:197], v[8:11]
	s_setprio 0
	s_barrier
	s_add_u32 s52, s62, 0x40000
	s_addc_u32 s53, s63, 0
	s_add_i32 s33, s89, s5
	s_mov_b32 m0, s33
	s_nop 0
	global_load_lds_dwordx4 v130, s[52:53]
	s_add_i32 m0, s33, 0x2000
	s_nop 0
	global_load_lds_dwordx4 v134, s[52:53]
	s_waitcnt vmcnt(6)
	s_barrier
; #define PG8_STAGE(bufoff, gbase, voff) do { _Pragma("unroll") for (int _i = 0; _i < 2; ++_i) \
;         __builtin_amdgcn_global_load_lds((const unsigned*)((const char*)(gbase) + (voff)[_i]), (LAS unsigned*)(lds + (bufoff) + ldsw + _i * 8192), 16, 0, 0); } while (0)
; #define PG8_LDA(dst, b, h) do { _Pragma("unroll") for (int m = 0; m < 4; ++m) _Pragma("unroll") for (int k = 0; k < 2; ++k) dst[m][k] = *(const LAS bf16x8*)(lds + PG8_SA(b, h) + aoff + m * 2048 + k * 1024); } while (0)
; #define PG8_LDB(dst, b, h) do { _Pragma("unroll") for (int n = 0; n < 2; ++n) _Pragma("unroll") for (int k = 0; k < 2; ++k) dst[n][k] = *(const LAS bf16x8*)(lds + PG8_SB(b, h) + boff + n * 2048 + k * 1024); } while (0)
; #define PG8_WAIT_V(n) asm volatile("s_waitcnt vmcnt(" #n ")" ::: "memory")
; #define PG8_WAIT_L(n) asm volatile("s_waitcnt lgkmcnt(" #n ")" ::: "memory")
; #define PG8_BAR __builtin_amdgcn_s_barrier()
; #define PG8_SCHED __builtin_amdgcn_sched_barrier(0)
; template <class Epi, class S_t>
; __device__ __forceinline__ void gemm_phase(LAS unsigned char* lds, int lda, int ldb, const S_t& S, const Epi& E) {
;     ...
;             PG8_LDB(B0, 0, 0); PG8_SCHED; PG8_LDA(At, 0, 0); PG8_STAGE(PG8_SA(1, 1), a1 + hstepA, voffA);
;             PG8_WAIT_L(8); PG8_BAR; PG8_WAIT_L(0); PG8_MMA(0, 0, At, B0); PG8_BAR; PG8_SCHED;
;             PG8_LDB(B1, 0, 1); PG8_STAGE(PG8_SB(0, 0), b2, voffB);
;             PG8_BAR; PG8_WAIT_L(0); PG8_MMA(0, 1, At, B1); PG8_BAR;
;             PG8_LDA(At, 0, 1); PG8_STAGE(PG8_SA(0, 0), a2, voffA);
;             PG8_BAR; PG8_WAIT_L(0); PG8_MMA(1, 0, At, B0); PG8_BAR; PG8_SCHED;
;             PG8_STAGE(PG8_SB(0, 1), b2 + hstepB, voffB);
;             PG8_WAIT_V(6); PG8_BAR; PG8_MMA(1, 1, At, B1); PG8_BAR;
;             PG8_LDB(B0, 1, 0); PG8_SCHED; PG8_LDA(At, 1, 0); PG8_STAGE(PG8_SA(0, 1), a2 + hstepA, voffA);
;             PG8_WAIT_L(8); PG8_BAR; PG8_WAIT_L(0); PG8_MMA(0, 0, At, B0); PG8_BAR; PG8_SCHED;
;             PG8_LDB(B1, 1, 1); PG8_STAGE(PG8_SB(1, 0), b3, voffB);
;             PG8_BAR; PG8_WAIT_L(0); PG8_MMA(0, 1, At, B1); PG8_BAR;
;             PG8_LDA(At, 1, 1); PG8_STAGE(PG8_SA(1, 0), a3, voffA);
;             PG8_BAR; PG8_WAIT_L(0); PG8_MMA(1, 0, At, B0); PG8_BAR; PG8_SCHED;
;             PG8_STAGE(PG8_SB(1, 1), b3 + hstepB, voffB);
;             PG8_WAIT_V(6); PG8_BAR; PG8_MMA(1, 1, At, B1); PG8_BAR;
	s_setprio 1
	v_mfma_f32_16x16x32_bf16 v[52:55], v[198:201], v[164:167], v[52:55]
	v_mfma_f32_16x16x32_bf16 v[44:47], v[206:209], v[164:167], v[44:47]
	v_mfma_f32_16x16x32_bf16 v[36:39], v[198:201], v[172:175], v[36:39]
	v_mfma_f32_16x16x32_bf16 v[28:31], v[206:209], v[172:175], v[28:31]
	v_mfma_f32_16x16x32_bf16 v[20:23], v[198:201], v[180:183], v[20:23]
	v_mfma_f32_16x16x32_bf16 v[12:15], v[206:209], v[180:183], v[12:15]
	v_mfma_f32_16x16x32_bf16 v[4:7], v[198:201], v[190:193], v[4:7]
	v_mfma_f32_16x16x32_bf16 v[0:3], v[206:209], v[190:193], v[0:3]
	v_mfma_f32_16x16x32_bf16 v[52:55], v[202:205], v[168:171], v[52:55]
	v_mfma_f32_16x16x32_bf16 v[44:47], v[222:225], v[168:171], v[44:47]
	v_mfma_f32_16x16x32_bf16 v[36:39], v[202:205], v[176:179], v[36:39]
	v_mfma_f32_16x16x32_bf16 v[28:31], v[222:225], v[176:179], v[28:31]
	v_mfma_f32_16x16x32_bf16 v[20:23], v[202:205], v[186:189], v[20:23]
	v_mfma_f32_16x16x32_bf16 v[12:15], v[222:225], v[186:189], v[12:15]
	v_mfma_f32_16x16x32_bf16 v[4:7], v[202:205], v[194:197], v[4:7]
	v_mfma_f32_16x16x32_bf16 v[0:3], v[222:225], v[194:197], v[0:3]
	s_setprio 0
	v_add_u32_e32 v160, s90, v147
	s_barrier
	ds_read_b128 v[140:143], v160
	ds_read_b128 v[152:155], v160 offset:1024
	ds_read_b128 v[156:159], v160 offset:2048
	ds_read_b128 v[160:163], v160 offset:3072
	s_add_u32 s52, s66, 0x40000
	s_addc_u32 s53, s67, 0
	s_mov_b32 m0, s20
	ds_read_b128 v[164:167], v150 offset:32768
	ds_read_b128 v[168:171], v150 offset:33792
	ds_read_b128 v[172:175], v150 offset:34816
	ds_read_b128 v[176:179], v150 offset:35840
	ds_read_b128 v[180:183], v150 offset:36864
	ds_read_b128 v[186:189], v150 offset:37888
	ds_read_b128 v[190:193], v150 offset:38912
	ds_read_b128 v[194:197], v150 offset:39936
	global_load_lds_dwordx4 v128, s[52:53]
	s_mov_b32 m0, s21
	s_nop 0
	global_load_lds_dwordx4 v132, s[52:53]
	s_waitcnt lgkmcnt(8)
	s_barrier
	s_waitcnt lgkmcnt(0)
	s_setprio 1
	s_waitcnt lgkmcnt(0)
	v_mfma_f32_16x16x32_bf16 v[124:127], v[140:143], v[164:167], v[124:127]
	v_mfma_f32_16x16x32_bf16 v[120:123], v[156:159], v[164:167], v[120:123]
	v_mfma_f32_16x16x32_bf16 v[116:119], v[140:143], v[172:175], v[116:119]
	v_mfma_f32_16x16x32_bf16 v[108:111], v[156:159], v[172:175], v[108:111]
	v_mfma_f32_16x16x32_bf16 v[96:99], v[140:143], v[180:183], v[96:99]
	v_mfma_f32_16x16x32_bf16 v[88:91], v[156:159], v[180:183], v[88:91]
	v_mfma_f32_16x16x32_bf16 v[80:83], v[140:143], v[190:193], v[80:83]
	v_mfma_f32_16x16x32_bf16 v[72:75], v[156:159], v[190:193], v[72:75]
	v_mfma_f32_16x16x32_bf16 v[124:127], v[152:155], v[168:171], v[124:127]
	v_mfma_f32_16x16x32_bf16 v[120:123], v[160:163], v[168:171], v[120:123]
	v_mfma_f32_16x16x32_bf16 v[116:119], v[152:155], v[176:179], v[116:119]
	v_mfma_f32_16x16x32_bf16 v[108:111], v[160:163], v[176:179], v[108:111]
	v_mfma_f32_16x16x32_bf16 v[96:99], v[152:155], v[186:189], v[96:99]
	v_mfma_f32_16x16x32_bf16 v[88:91], v[160:163], v[186:189], v[88:91]
	v_mfma_f32_16x16x32_bf16 v[80:83], v[152:155], v[194:197], v[80:83]
	v_mfma_f32_16x16x32_bf16 v[72:75], v[160:163], v[194:197], v[72:75]
	s_setprio 0
	s_barrier
	s_add_i32 s33, s90, s5
	v_add_u32_e32 v185, s91, v147
	s_mov_b32 m0, s33
	ds_read_b128 v[198:201], v185
	ds_read_b128 v[202:205], v185 offset:1024
	ds_read_b128 v[206:209], v185 offset:2048
	ds_read_b128 v[222:225], v185 offset:3072
	global_load_lds_dwordx4 v130, s[98:99]
	s_add_i32 m0, s33, 0x2000
	s_nop 0
	global_load_lds_dwordx4 v134, s[98:99]
	s_barrier
	s_waitcnt lgkmcnt(0)
	s_setprio 1
	s_waitcnt lgkmcnt(0)
	v_mfma_f32_16x16x32_bf16 v[112:115], v[198:201], v[164:167], v[112:115]
	v_mfma_f32_16x16x32_bf16 v[104:107], v[206:209], v[164:167], v[104:107]
	v_mfma_f32_16x16x32_bf16 v[100:103], v[198:201], v[172:175], v[100:103]
	v_mfma_f32_16x16x32_bf16 v[92:95], v[206:209], v[172:175], v[92:95]
	v_mfma_f32_16x16x32_bf16 v[84:87], v[198:201], v[180:183], v[84:87]
	v_mfma_f32_16x16x32_bf16 v[76:79], v[206:209], v[180:183], v[76:79]
	v_mfma_f32_16x16x32_bf16 v[68:71], v[198:201], v[190:193], v[68:71]
	v_mfma_f32_16x16x32_bf16 v[64:67], v[206:209], v[190:193], v[64:67]
	v_mfma_f32_16x16x32_bf16 v[112:115], v[202:205], v[168:171], v[112:115]
	v_mfma_f32_16x16x32_bf16 v[104:107], v[222:225], v[168:171], v[104:107]
	v_mfma_f32_16x16x32_bf16 v[100:103], v[202:205], v[176:179], v[100:103]
	v_mfma_f32_16x16x32_bf16 v[92:95], v[222:225], v[176:179], v[92:95]
	v_mfma_f32_16x16x32_bf16 v[84:87], v[202:205], v[186:189], v[84:87]
	v_mfma_f32_16x16x32_bf16 v[76:79], v[222:225], v[186:189], v[76:79]
	v_mfma_f32_16x16x32_bf16 v[68:71], v[202:205], v[194:197], v[68:71]
	v_mfma_f32_16x16x32_bf16 v[64:67], v[222:225], v[194:197], v[64:67]
	s_setprio 0
	s_mov_b32 m0, s35
	s_barrier
	ds_read_b128 v[164:167], v150 offset:49152
	ds_read_b128 v[168:171], v150 offset:50176
	ds_read_b128 v[172:175], v150 offset:51200
	ds_read_b128 v[176:179], v150 offset:52224
	ds_read_b128 v[180:183], v150 offset:53248
	ds_read_b128 v[186:189], v150 offset:54272
	ds_read_b128 v[190:193], v150 offset:55296
	ds_read_b128 v[194:197], v150 offset:56320
	global_load_lds_dwordx4 v128, s[100:101]
	s_mov_b32 m0, s64
	s_nop 0
	global_load_lds_dwordx4 v132, s[100:101]
	s_barrier
; #define PG8_STAGE(bufoff, gbase, voff) do { _Pragma("unroll") for (int _i = 0; _i < 2; ++_i) \
;         __builtin_amdgcn_global_load_lds((const unsigned*)((const char*)(gbase) + (voff)[_i]), (LAS unsigned*)(lds + (bufoff) + ldsw + _i * 8192), 16, 0, 0); } while (0)
; #define PG8_LDA(dst, b, h) do { _Pragma("unroll") for (int m = 0; m < 4; ++m) _Pragma("unroll") for (int k = 0; k < 2; ++k) dst[m][k] = *(const LAS bf16x8*)(lds + PG8_SA(b, h) + aoff + m * 2048 + k * 1024); } while (0)
; #define PG8_LDB(dst, b, h) do { _Pragma("unroll") for (int n = 0; n < 2; ++n) _Pragma("unroll") for (int k = 0; k < 2; ++k) dst[n][k] = *(const LAS bf16x8*)(lds + PG8_SB(b, h) + boff + n * 2048 + k * 1024); } while (0)
; #define PG8_WAIT_V(n) asm volatile("s_waitcnt vmcnt(" #n ")" ::: "memory")
; #define PG8_BAR __builtin_amdgcn_s_barrier()
; template <class Epi, class S_t>
; __device__ __forceinline__ void gemm_phase(LAS unsigned char* lds, int lda, int ldb, const S_t& S, const Epi& E) {
;     ...
;             PG8_WAIT_V(6); PG8_BAR; PG8_MMA(1, 1, At, B1); PG8_BAR;
;             PG8_LDB(B0, 1, 0); PG8_SCHED; PG8_LDA(At, 1, 0); PG8_STAGE(PG8_SA(0, 1), a2 + hstepA, voffA);
;             PG8_WAIT_L(8); PG8_BAR; PG8_WAIT_L(0); PG8_MMA(0, 0, At, B0); PG8_BAR; PG8_SCHED;
;             PG8_LDB(B1, 1, 1); PG8_STAGE(PG8_SB(1, 0), b3, voffB);
;             PG8_BAR; PG8_WAIT_L(0); PG8_MMA(0, 1, At, B1); PG8_BAR;
;             PG8_LDA(At, 1, 1); PG8_STAGE(PG8_SA(1, 0), a3, voffA);
;             PG8_BAR; PG8_WAIT_L(0); PG8_MMA(1, 0, At, B0); PG8_BAR; PG8_SCHED;
;             PG8_STAGE(PG8_SB(1, 1), b3 + hstepB, voffB);
;             PG8_WAIT_V(6); PG8_BAR; PG8_MMA(1, 1, At, B1); PG8_BAR;
;         }
;         E(acc, cur, wr, wc, fr, fq);
;     __device__ __forceinline__ void operator()(const f32x4 (&acc)[2][2][4][2], const Unit& u, int wr, int wc, int fr, int fq) const {
;     ...
; #pragma unroll
;         for (int ai = 0; ai < 2; ++ai) {
;             u32x4 gr[4][2], orw[4][2];
;             asm volatile("" ::: "memory");
; #pragma unroll
;             for (int m = 0; m < 4; ++m)
; #pragma unroll
;                 for (int bj = 0; bj < 2; ++bj) { const int row = row0 + ai * HALF + m * 16, col = col0 + bj * HALF;
;                     gr[m][bj] = *(const u32x4*)(Z + (size_t)row * INW + gcol0 + col);
;                     if (ADD) orw[m][bj] = *(const u32x4*)(MG + (size_t)row * DM + col); }
	s_waitcnt lgkmcnt(0)
	s_setprio 1
	s_waitcnt lgkmcnt(0)
	v_mfma_f32_16x16x32_bf16 v[60:63], v[140:143], v[164:167], v[60:63]
	v_mfma_f32_16x16x32_bf16 v[56:59], v[156:159], v[164:167], v[56:59]
	v_mfma_f32_16x16x32_bf16 v[48:51], v[140:143], v[172:175], v[48:51]
	v_mfma_f32_16x16x32_bf16 v[40:43], v[156:159], v[172:175], v[40:43]
	v_mfma_f32_16x16x32_bf16 v[32:35], v[140:143], v[180:183], v[32:35]
	v_mfma_f32_16x16x32_bf16 v[24:27], v[156:159], v[180:183], v[24:27]
	v_mfma_f32_16x16x32_bf16 v[16:19], v[140:143], v[190:193], v[16:19]
	v_mfma_f32_16x16x32_bf16 v[8:11], v[156:159], v[190:193], v[8:11]
	v_mfma_f32_16x16x32_bf16 v[60:63], v[152:155], v[168:171], v[60:63]
	v_mfma_f32_16x16x32_bf16 v[56:59], v[160:163], v[168:171], v[56:59]
	v_mfma_f32_16x16x32_bf16 v[48:51], v[152:155], v[176:179], v[48:51]
	v_mfma_f32_16x16x32_bf16 v[40:43], v[160:163], v[176:179], v[40:43]
	v_mfma_f32_16x16x32_bf16 v[32:35], v[152:155], v[186:189], v[32:35]
	v_mfma_f32_16x16x32_bf16 v[24:27], v[160:163], v[186:189], v[24:27]
	v_mfma_f32_16x16x32_bf16 v[16:19], v[152:155], v[194:197], v[16:19]
	v_mfma_f32_16x16x32_bf16 v[8:11], v[160:163], v[194:197], v[8:11]
	s_setprio 0
	s_barrier
	s_add_u32 s52, s62, 0x40080
	s_addc_u32 s53, s63, 0
	s_add_i32 s33, s91, s5
	s_mov_b32 m0, s33
	s_nop 0
	global_load_lds_dwordx4 v130, s[52:53]
	s_add_i32 m0, s33, 0x2000
	s_nop 0
	global_load_lds_dwordx4 v134, s[52:53]
	s_waitcnt vmcnt(6)
	s_barrier
	s_setprio 1
	v_mfma_f32_16x16x32_bf16 v[52:55], v[198:201], v[164:167], v[52:55]
	v_mfma_f32_16x16x32_bf16 v[44:47], v[206:209], v[164:167], v[44:47]
	v_mfma_f32_16x16x32_bf16 v[36:39], v[198:201], v[172:175], v[36:39]
	v_mfma_f32_16x16x32_bf16 v[28:31], v[206:209], v[172:175], v[28:31]
	v_mfma_f32_16x16x32_bf16 v[20:23], v[198:201], v[180:183], v[20:23]
	v_mfma_f32_16x16x32_bf16 v[12:15], v[206:209], v[180:183], v[12:15]
	v_mfma_f32_16x16x32_bf16 v[4:7], v[198:201], v[190:193], v[4:7]
	v_mfma_f32_16x16x32_bf16 v[0:3], v[206:209], v[190:193], v[0:3]
	v_mfma_f32_16x16x32_bf16 v[52:55], v[202:205], v[168:171], v[52:55]
	v_mfma_f32_16x16x32_bf16 v[44:47], v[222:225], v[168:171], v[44:47]
	v_mfma_f32_16x16x32_bf16 v[36:39], v[202:205], v[176:179], v[36:39]
	v_mfma_f32_16x16x32_bf16 v[28:31], v[222:225], v[176:179], v[28:31]
	v_mfma_f32_16x16x32_bf16 v[20:23], v[202:205], v[186:189], v[20:23]
	v_mfma_f32_16x16x32_bf16 v[12:15], v[222:225], v[186:189], v[12:15]
	v_mfma_f32_16x16x32_bf16 v[4:7], v[202:205], v[194:197], v[4:7]
	v_mfma_f32_16x16x32_bf16 v[0:3], v[222:225], v[194:197], v[0:3]
	s_setprio 0
	s_add_i32 s43, s43, 2
	s_add_u32 s60, s60, 0x100
	s_addc_u32 s61, s61, 0
	s_add_u32 s0, s0, 0x100
	s_addc_u32 s1, s1, 0
	s_cmp_gt_u32 s43, 13
	s_barrier
	s_cbranch_scc0 .LBB0_945
	v_lshl_or_b32 v140, s42, 8, v148
	v_lshl_add_u32 v142, s8, 8, v146
	v_ashrrev_i32_e32 v141, 31, v140
	v_mov_b64_e32 v[144:145], s[46:47]
	v_mad_i64_i32 v[152:153], s[0:1], v142, s69, v[144:145]
	v_lshlrev_b64 v[140:141], 1, v[140:141]
	v_or_b32_e32 v168, 16, v142
	v_lshl_add_u64 v[156:157], v[152:153], 0, v[140:141]
	v_mad_i64_i32 v[160:161], s[0:1], v168, s69, v[144:145]
	global_load_dwordx4 v[152:155], v[156:157], off
	s_nop 0
	global_load_dwordx4 v[156:159], v[156:157], off offset:256
	v_lshl_add_u64 v[164:165], v[160:161], 0, v[140:141]
	global_load_dwordx4 v[160:163], v[164:165], off
	v_or_b32_e32 v186, 32, v142
	global_load_dwordx4 v[164:167], v[164:165], off offset:256
	v_or_b32_e32 v188, 48, v142
	v_ashrrev_i32_e32 v143, 31, v142
	v_mad_i64_i32 v[170:171], s[0:1], v186, s69, v[144:145]
	v_mad_i64_i32 v[172:173], s[0:1], v188, s69, v[144:145]
	v_ashrrev_i32_e32 v169, 31, v168
	v_lshlrev_b64 v[174:175], 12, v[142:143]
	v_lshl_add_u64 v[176:177], v[170:171], 0, v[140:141]
	v_lshl_add_u64 v[180:181], v[172:173], 0, v[140:141]
	v_lshl_add_u64 v[190:191], s[44:45], 0, v[174:175]
	v_lshlrev_b64 v[192:193], 12, v[168:169]
	global_load_dwordx4 v[168:171], v[176:177], off
	global_load_dwordx4 v[172:175], v[176:177], off offset:256
	s_nop 0
	global_load_dwordx4 v[176:179], v[180:181], off
	s_nop 0
	global_load_dwordx4 v[180:183], v[180:181], off offset:256
	v_lshl_add_u64 v[190:191], v[190:191], 0, v[140:141]
	v_ashrrev_i32_e32 v187, 31, v186
	v_ashrrev_i32_e32 v189, 31, v188
	s_cmpk_lt_i32 s70, 0x3e8
	s_waitcnt vmcnt(0)
; __device__ __forceinline__ u32x4 pack8(const float (&f)[8]) { u32x4 w; w.x = pk2(f[0], f[1]); w.y = pk2(f[2], f[3]); w.z = pk2(f[4], f[5]); w.w = pk2(f[6], f[7]); return w; }
;     __device__ __forceinline__ void operator()(const f32x4 (&acc)[2][2][4][2], const Unit& u, int wr, int wc, int fr, int fq) const {
;     ...
; #pragma unroll
;             for (int m = 0; m < 4; ++m)
; #pragma unroll
;                 for (int bj = 0; bj < 2; ++bj) { const int row = row0 + ai * HALF + m * 16, col = col0 + bj * HALF;
;                     float g[8], o[8]; unpack8(gr[m][bj], g);
;                     if (ADD) unpack8(orw[m][bj], o);
; #pragma unroll
;                     for (int n = 0; n < 2; ++n)
; #pragma unroll
;                         for (int j = 0; j < 4; ++j) { const int e = 4 * n + j; o[e] = ADD ? o[e] + g[e] * acc[ai][bj][m][n][j] : g[e] * acc[ai][bj][m][n][j]; }
;                     *(u32x4*)(MG + (size_t)row * DM + col) = pack8(o); }
	v_lshlrev_b32_e32 v143, 16, v152
	v_and_b32_e32 v152, 0xffff0000, v152
	v_lshlrev_b32_e32 v185, 16, v153
	v_and_b32_e32 v153, 0xffff0000, v153
	v_lshlrev_b32_e32 v194, 16, v154
	v_and_b32_e32 v154, 0xffff0000, v154
	v_lshlrev_b32_e32 v195, 16, v155
	v_and_b32_e32 v155, 0xffff0000, v155
	v_lshlrev_b32_e32 v196, 16, v156
	v_and_b32_e32 v156, 0xffff0000, v156
	v_lshlrev_b32_e32 v197, 16, v157
	v_and_b32_e32 v157, 0xffff0000, v157
	v_lshlrev_b32_e32 v198, 16, v158
	v_and_b32_e32 v158, 0xffff0000, v158
	v_lshlrev_b32_e32 v199, 16, v159
	v_and_b32_e32 v159, 0xffff0000, v159
	v_lshlrev_b32_e32 v200, 16, v160
	v_and_b32_e32 v160, 0xffff0000, v160
	v_lshlrev_b32_e32 v201, 16, v161
	v_lshlrev_b32_e32 v202, 16, v162
	v_and_b32_e32 v162, 0xffff0000, v162
	v_mul_f32_e32 v124, v124, v143
	v_mul_f32_e32 v125, v125, v152
	v_mul_f32_e32 v126, v126, v185
	v_mul_f32_e32 v127, v127, v153
	v_mul_f32_e32 v120, v120, v194
	v_mul_f32_e32 v121, v121, v154
	v_mul_f32_e32 v122, v122, v195
	v_mul_f32_e32 v123, v123, v155
	v_mul_f32_e32 v112, v112, v196
	v_mul_f32_e32 v113, v113, v156
	v_mul_f32_e32 v114, v114, v197
	v_mul_f32_e32 v115, v115, v157
	v_mul_f32_e32 v143, v104, v198
	v_mul_f32_e32 v152, v105, v158
	v_mul_f32_e32 v153, v106, v199
	v_mul_f32_e32 v154, v107, v159
	v_cvt_pk_bf16_f32 v104, v124, v125
	v_cvt_pk_bf16_f32 v105, v126, v127
	v_cvt_pk_bf16_f32 v106, v120, v121
	v_cvt_pk_bf16_f32 v107, v122, v123
	v_and_b32_e32 v161, 0xffff0000, v161
	v_cvt_pk_bf16_f32 v112, v112, v113
	v_cvt_pk_bf16_f32 v113, v114, v115
	v_cvt_pk_bf16_f32 v114, v143, v152
	v_cvt_pk_bf16_f32 v115, v153, v154
	global_store_dwordx4 v[190:191], v[104:107], off
	global_store_dwordx4 v[190:191], v[112:115], off offset:256
	v_mul_f32_e32 v108, v108, v202
	v_mul_f32_e32 v104, v116, v200
	v_mul_f32_e32 v105, v117, v160
	v_mul_f32_e32 v106, v118, v201
	v_mul_f32_e32 v109, v109, v162
	v_lshlrev_b32_e32 v203, 16, v163
	v_and_b32_e32 v163, 0xffff0000, v163
	v_mul_f32_e32 v107, v119, v161
	v_cvt_pk_bf16_f32 v104, v104, v105
	v_cvt_pk_bf16_f32 v105, v106, v107
	v_cvt_pk_bf16_f32 v106, v108, v109
	v_lshl_add_u64 v[108:109], s[44:45], 0, v[192:193]
	v_mul_f32_e32 v110, v110, v203
	v_mul_f32_e32 v111, v111, v163
	v_cvt_pk_bf16_f32 v107, v110, v111
	v_lshl_add_u64 v[108:109], v[108:109], 0, v[140:141]
	global_store_dwordx4 v[108:109], v[104:107], off
	v_lshlrev_b32_e32 v110, 16, v166
	v_and_b32_e32 v111, 0xffff0000, v166
	v_lshlrev_b32_e32 v104, 16, v164
	v_and_b32_e32 v105, 0xffff0000, v164
	v_lshlrev_b32_e32 v106, 16, v165
	v_and_b32_e32 v107, 0xffff0000, v165
	v_and_b32_e32 v113, 0xffff0000, v167
	v_lshlrev_b32_e32 v112, 16, v167
	v_mul_f32_e32 v100, v100, v104
	v_mul_f32_e32 v101, v101, v105
	v_mul_f32_e32 v102, v102, v106
	v_mul_f32_e32 v103, v103, v107
	v_mul_f32_e32 v104, v92, v110
	v_mul_f32_e32 v105, v93, v111
	v_mul_f32_e32 v95, v95, v113
	v_cvt_pk_bf16_f32 v92, v100, v101
	v_cvt_pk_bf16_f32 v93, v102, v103
	v_mul_f32_e32 v106, v94, v112
	v_cvt_pk_bf16_f32 v94, v104, v105
	v_cvt_pk_bf16_f32 v95, v106, v95
	global_store_dwordx4 v[108:109], v[92:95], off offset:256
	v_and_b32_e32 v105, 0xffff0000, v171
	v_lshlrev_b32_e32 v100, 16, v169
	v_lshlrev_b64 v[92:93], 12, v[186:187]
	v_lshlrev_b32_e32 v94, 16, v168
	v_and_b32_e32 v95, 0xffff0000, v168
	v_and_b32_e32 v101, 0xffff0000, v169
	v_lshlrev_b32_e32 v102, 16, v170
	v_and_b32_e32 v103, 0xffff0000, v170
	v_lshlrev_b32_e32 v104, 16, v171
	v_mul_f32_e32 v91, v91, v105
	v_lshl_add_u64 v[92:93], s[44:45], 0, v[92:93]
	v_mul_f32_e32 v94, v96, v94
	v_mul_f32_e32 v95, v97, v95
	v_mul_f32_e32 v96, v98, v100
	v_mul_f32_e32 v97, v99, v101
	v_mul_f32_e32 v98, v88, v102
	v_mul_f32_e32 v99, v89, v103
	v_mul_f32_e32 v100, v90, v104
	v_cvt_pk_bf16_f32 v88, v94, v95
	v_cvt_pk_bf16_f32 v89, v96, v97
	v_cvt_pk_bf16_f32 v90, v98, v99
	v_cvt_pk_bf16_f32 v91, v100, v91
	v_lshl_add_u64 v[92:93], v[92:93], 0, v[140:141]
	global_store_dwordx4 v[92:93], v[88:91], off
	v_lshlrev_b32_e32 v94, 16, v174
	v_and_b32_e32 v95, 0xffff0000, v174
	v_lshlrev_b32_e32 v88, 16, v172
	v_and_b32_e32 v89, 0xffff0000, v172
	v_lshlrev_b32_e32 v90, 16, v173
	v_and_b32_e32 v91, 0xffff0000, v173
	v_and_b32_e32 v97, 0xffff0000, v175
	v_lshlrev_b32_e32 v96, 16, v175
	v_mul_f32_e32 v84, v84, v88
	v_mul_f32_e32 v85, v85, v89
	v_mul_f32_e32 v86, v86, v90
	v_mul_f32_e32 v87, v87, v91
	v_mul_f32_e32 v88, v76, v94
	v_mul_f32_e32 v89, v77, v95
	v_mul_f32_e32 v79, v79, v97
	v_cvt_pk_bf16_f32 v76, v84, v85
	v_cvt_pk_bf16_f32 v77, v86, v87
	v_mul_f32_e32 v90, v78, v96
	v_cvt_pk_bf16_f32 v78, v88, v89
	v_cvt_pk_bf16_f32 v79, v90, v79
	global_store_dwordx4 v[92:93], v[76:79], off offset:256
	v_and_b32_e32 v89, 0xffff0000, v179
	v_lshlrev_b32_e32 v84, 16, v177
	v_lshlrev_b64 v[76:77], 12, v[188:189]
	v_lshlrev_b32_e32 v78, 16, v176
	v_and_b32_e32 v79, 0xffff0000, v176
	v_and_b32_e32 v85, 0xffff0000, v177
	v_lshlrev_b32_e32 v86, 16, v178
	v_and_b32_e32 v87, 0xffff0000, v178
	v_lshlrev_b32_e32 v88, 16, v179
	v_mul_f32_e32 v75, v75, v89
	v_lshl_add_u64 v[76:77], s[44:45], 0, v[76:77]
	v_mul_f32_e32 v78, v80, v78
	v_mul_f32_e32 v79, v81, v79
	v_mul_f32_e32 v80, v82, v84
	v_mul_f32_e32 v81, v83, v85
	v_mul_f32_e32 v82, v72, v86
	v_mul_f32_e32 v83, v73, v87
	v_mul_f32_e32 v84, v74, v88
	v_cvt_pk_bf16_f32 v72, v78, v79
	v_cvt_pk_bf16_f32 v73, v80, v81
	v_cvt_pk_bf16_f32 v74, v82, v83
	v_cvt_pk_bf16_f32 v75, v84, v75
	v_lshl_add_u64 v[76:77], v[76:77], 0, v[140:141]
	global_store_dwordx4 v[76:77], v[72:75], off
	v_lshlrev_b32_e32 v78, 16, v182
	v_and_b32_e32 v79, 0xffff0000, v182
	v_lshlrev_b32_e32 v72, 16, v180
	v_and_b32_e32 v73, 0xffff0000, v180
	v_lshlrev_b32_e32 v74, 16, v181
	v_and_b32_e32 v75, 0xffff0000, v181
; __device__ __forceinline__ u32x4 pack8(const float (&f)[8]) { u32x4 w; w.x = pk2(f[0], f[1]); w.y = pk2(f[2], f[3]); w.z = pk2(f[4], f[5]); w.w = pk2(f[6], f[7]); return w; }
;     __device__ __forceinline__ void operator()(const f32x4 (&acc)[2][2][4][2], const Unit& u, int wr, int wc, int fr, int fq) const {
;     ...
;             u32x4 gr[4][2], orw[4][2];
;             asm volatile("" ::: "memory");
; #pragma unroll
;             for (int m = 0; m < 4; ++m)
; #pragma unroll
;                 for (int bj = 0; bj < 2; ++bj) { const int row = row0 + ai * HALF + m * 16, col = col0 + bj * HALF;
;                     gr[m][bj] = *(const u32x4*)(Z + (size_t)row * INW + gcol0 + col);
;                     if (ADD) orw[m][bj] = *(const u32x4*)(MG + (size_t)row * DM + col); }
;             asm volatile("" ::: "memory");
; #pragma unroll
;             for (int m = 0; m < 4; ++m)
; #pragma unroll
;                 for (int bj = 0; bj < 2; ++bj) { const int row = row0 + ai * HALF + m * 16, col = col0 + bj * HALF;
;                     float g[8], o[8]; unpack8(gr[m][bj], g);
;                     if (ADD) unpack8(orw[m][bj], o);
; #pragma unroll
;                     for (int n = 0; n < 2; ++n)
; #pragma unroll
;                         for (int j = 0; j < 4; ++j) { const int e = 4 * n + j; o[e] = ADD ? o[e] + g[e] * acc[ai][bj][m][n][j] : g[e] * acc[ai][bj][m][n][j]; }
;                     *(u32x4*)(MG + (size_t)row * DM + col) = pack8(o); }
	v_and_b32_e32 v81, 0xffff0000, v183
	v_lshlrev_b32_e32 v80, 16, v183
	v_mul_f32_e32 v68, v68, v72
	v_mul_f32_e32 v69, v69, v73
	v_mul_f32_e32 v70, v70, v74
	v_mul_f32_e32 v71, v71, v75
	v_mul_f32_e32 v72, v64, v78
	v_mul_f32_e32 v73, v65, v79
	v_mul_f32_e32 v67, v67, v81
	v_cvt_pk_bf16_f32 v64, v68, v69
	v_cvt_pk_bf16_f32 v65, v70, v71
	v_add_u32_e32 v96, 0x80, v142
	v_mul_f32_e32 v74, v66, v80
	v_cvt_pk_bf16_f32 v66, v72, v73
	v_cvt_pk_bf16_f32 v67, v74, v67
	global_store_dwordx4 v[76:77], v[64:67], off offset:256
	v_add_u32_e32 v98, 0x90, v142
	v_mad_i64_i32 v[72:73], s[0:1], v98, s69, v[144:145]
	v_mad_i64_i32 v[64:65], s[0:1], v96, s69, v[144:145]
	v_lshl_add_u64 v[68:69], v[64:65], 0, v[140:141]
	global_load_dwordx4 v[64:67], v[68:69], off
	s_nop 0
	global_load_dwordx4 v[68:71], v[68:69], off offset:256
	v_lshl_add_u64 v[76:77], v[72:73], 0, v[140:141]
	global_load_dwordx4 v[72:75], v[76:77], off
	v_add_u32_e32 v100, 0xa0, v142
	global_load_dwordx4 v[76:79], v[76:77], off offset:256
	v_mad_i64_i32 v[80:81], s[0:1], v100, s69, v[144:145]
	v_lshl_add_u64 v[84:85], v[80:81], 0, v[140:141]
	global_load_dwordx4 v[80:83], v[84:85], off
	s_nop 0
	global_load_dwordx4 v[84:87], v[84:85], off offset:256
	v_add_u32_e32 v102, 0xb0, v142
	v_mad_i64_i32 v[88:89], s[0:1], v102, s69, v[144:145]
	v_lshl_add_u64 v[92:93], v[88:89], 0, v[140:141]
	global_load_dwordx4 v[88:91], v[92:93], off
	s_nop 0
	global_load_dwordx4 v[92:95], v[92:93], off offset:256
	v_ashrrev_i32_e32 v97, 31, v96
	v_lshlrev_b64 v[96:97], 12, v[96:97]
	v_ashrrev_i32_e32 v99, 31, v98
	v_ashrrev_i32_e32 v101, 31, v100
	v_ashrrev_i32_e32 v103, 31, v102
	s_waitcnt vmcnt(0)
; __device__ __forceinline__ u32x4 pack8(const float (&f)[8]) { u32x4 w; w.x = pk2(f[0], f[1]); w.y = pk2(f[2], f[3]); w.z = pk2(f[4], f[5]); w.w = pk2(f[6], f[7]); return w; }
;     __device__ __forceinline__ void operator()(const f32x4 (&acc)[2][2][4][2], const Unit& u, int wr, int wc, int fr, int fq) const {
;     ...
; #pragma unroll
;             for (int m = 0; m < 4; ++m)
; #pragma unroll
;                 for (int bj = 0; bj < 2; ++bj) { const int row = row0 + ai * HALF + m * 16, col = col0 + bj * HALF;
;                     float g[8], o[8]; unpack8(gr[m][bj], g);
;                     if (ADD) unpack8(orw[m][bj], o);
; #pragma unroll
;                     for (int n = 0; n < 2; ++n)
; #pragma unroll
;                         for (int j = 0; j < 4; ++j) { const int e = 4 * n + j; o[e] = ADD ? o[e] + g[e] * acc[ai][bj][m][n][j] : g[e] * acc[ai][bj][m][n][j]; }
;                     *(u32x4*)(MG + (size_t)row * DM + col) = pack8(o); }
;         }
;         if (!ADD && u.tag >= 1000) {
;             asm volatile("s_waitcnt vmcnt(0)" ::: "memory");
;             __builtin_amdgcn_fence(__ATOMIC_RELEASE, "agent");
;             asm volatile("s_waitcnt vmcnt(0)" ::: "memory");
;             if ((threadIdx.x & 63) == 0) __hip_atomic_fetch_add(flags + P7_FLAG(u.tag - 1000), 1u, __ATOMIC_RELAXED, __HIP_MEMORY_SCOPE_AGENT);
;         }
	v_lshlrev_b32_e32 v104, 16, v64
	v_and_b32_e32 v64, 0xffff0000, v64
	v_lshlrev_b32_e32 v105, 16, v65
	v_and_b32_e32 v65, 0xffff0000, v65
	v_lshlrev_b32_e32 v106, 16, v66
	v_and_b32_e32 v66, 0xffff0000, v66
	v_lshlrev_b32_e32 v107, 16, v67
	v_and_b32_e32 v67, 0xffff0000, v67
	v_mul_f32_e32 v60, v60, v104
	v_mul_f32_e32 v61, v61, v64
	v_mul_f32_e32 v63, v63, v65
	v_mul_f32_e32 v64, v56, v106
	v_mul_f32_e32 v65, v57, v66
	v_mul_f32_e32 v59, v59, v67
	v_cvt_pk_bf16_f32 v56, v60, v61
	v_lshl_add_u64 v[60:61], s[44:45], 0, v[96:97]
	v_mul_f32_e32 v62, v62, v105
	v_mul_f32_e32 v66, v58, v107
	v_cvt_pk_bf16_f32 v57, v62, v63
	v_cvt_pk_bf16_f32 v58, v64, v65
	v_cvt_pk_bf16_f32 v59, v66, v59
	v_lshl_add_u64 v[60:61], v[60:61], 0, v[140:141]
	v_and_b32_e32 v65, 0xffff0000, v71
	global_store_dwordx4 v[60:61], v[56:59], off
	v_lshlrev_b32_e32 v62, 16, v70
	v_and_b32_e32 v63, 0xffff0000, v70
	v_lshlrev_b32_e32 v56, 16, v68
	v_and_b32_e32 v57, 0xffff0000, v68
	v_lshlrev_b32_e32 v58, 16, v69
	v_and_b32_e32 v59, 0xffff0000, v69
	v_lshlrev_b32_e32 v64, 16, v71
	v_mul_f32_e32 v47, v47, v65
	v_mul_f32_e32 v52, v52, v56
	v_mul_f32_e32 v53, v53, v57
	v_mul_f32_e32 v54, v54, v58
	v_mul_f32_e32 v55, v55, v59
	v_mul_f32_e32 v56, v44, v62
	v_mul_f32_e32 v57, v45, v63
	v_mul_f32_e32 v58, v46, v64
	v_cvt_pk_bf16_f32 v44, v52, v53
	v_cvt_pk_bf16_f32 v45, v54, v55
	v_cvt_pk_bf16_f32 v47, v58, v47
	v_cvt_pk_bf16_f32 v46, v56, v57
	global_store_dwordx4 v[60:61], v[44:47], off offset:256
	v_and_b32_e32 v53, 0xffff0000, v73
	v_and_b32_e32 v57, 0xffff0000, v75
	v_lshlrev_b64 v[44:45], 12, v[98:99]
	v_and_b32_e32 v47, 0xffff0000, v72
	v_lshlrev_b32_e32 v46, 16, v72
	v_lshlrev_b32_e32 v52, 16, v73
	v_lshlrev_b32_e32 v54, 16, v74
	v_and_b32_e32 v55, 0xffff0000, v74
	v_lshlrev_b32_e32 v56, 16, v75
	v_mul_f32_e32 v47, v49, v47
	v_mul_f32_e32 v49, v51, v53
	v_mul_f32_e32 v43, v43, v57
	v_lshl_add_u64 v[44:45], s[44:45], 0, v[44:45]
	v_mul_f32_e32 v46, v48, v46
	v_mul_f32_e32 v48, v50, v52
	v_mul_f32_e32 v50, v40, v54
	v_mul_f32_e32 v51, v41, v55
	v_mul_f32_e32 v52, v42, v56
	v_cvt_pk_bf16_f32 v40, v46, v47
	v_cvt_pk_bf16_f32 v41, v48, v49
	v_cvt_pk_bf16_f32 v42, v50, v51
	v_cvt_pk_bf16_f32 v43, v52, v43
	v_lshl_add_u64 v[44:45], v[44:45], 0, v[140:141]
	v_and_b32_e32 v49, 0xffff0000, v79
	global_store_dwordx4 v[44:45], v[40:43], off
	v_lshlrev_b32_e32 v46, 16, v78
	v_and_b32_e32 v47, 0xffff0000, v78
	v_lshlrev_b32_e32 v40, 16, v76
	v_and_b32_e32 v41, 0xffff0000, v76
	v_lshlrev_b32_e32 v42, 16, v77
	v_and_b32_e32 v43, 0xffff0000, v77
	v_lshlrev_b32_e32 v48, 16, v79
	v_mul_f32_e32 v31, v31, v49
	v_mul_f32_e32 v36, v36, v40
	v_mul_f32_e32 v37, v37, v41
	v_mul_f32_e32 v38, v38, v42
	v_mul_f32_e32 v39, v39, v43
	v_mul_f32_e32 v40, v28, v46
	v_mul_f32_e32 v41, v29, v47
	v_mul_f32_e32 v42, v30, v48
	v_cvt_pk_bf16_f32 v28, v36, v37
	v_cvt_pk_bf16_f32 v29, v38, v39
	v_cvt_pk_bf16_f32 v31, v42, v31
	v_cvt_pk_bf16_f32 v30, v40, v41
	global_store_dwordx4 v[44:45], v[28:31], off offset:256
	v_and_b32_e32 v37, 0xffff0000, v81
	v_and_b32_e32 v41, 0xffff0000, v83
	v_lshlrev_b64 v[28:29], 12, v[100:101]
	v_and_b32_e32 v31, 0xffff0000, v80
	v_lshlrev_b32_e32 v30, 16, v80
	v_lshlrev_b32_e32 v36, 16, v81
	v_lshlrev_b32_e32 v38, 16, v82
	v_and_b32_e32 v39, 0xffff0000, v82
	v_lshlrev_b32_e32 v40, 16, v83
	v_mul_f32_e32 v31, v33, v31
	v_mul_f32_e32 v33, v35, v37
	v_mul_f32_e32 v27, v27, v41
	v_lshl_add_u64 v[28:29], s[44:45], 0, v[28:29]
	v_mul_f32_e32 v30, v32, v30
	v_mul_f32_e32 v32, v34, v36
	v_mul_f32_e32 v34, v24, v38
	v_mul_f32_e32 v35, v25, v39
	v_mul_f32_e32 v36, v26, v40
	v_cvt_pk_bf16_f32 v24, v30, v31
	v_cvt_pk_bf16_f32 v25, v32, v33
	v_cvt_pk_bf16_f32 v26, v34, v35
	v_cvt_pk_bf16_f32 v27, v36, v27
	v_lshl_add_u64 v[28:29], v[28:29], 0, v[140:141]
	v_and_b32_e32 v33, 0xffff0000, v87
	global_store_dwordx4 v[28:29], v[24:27], off
	v_lshlrev_b32_e32 v30, 16, v86
	v_and_b32_e32 v31, 0xffff0000, v86
	v_lshlrev_b32_e32 v24, 16, v84
	v_and_b32_e32 v25, 0xffff0000, v84
	v_lshlrev_b32_e32 v26, 16, v85
	v_and_b32_e32 v27, 0xffff0000, v85
	v_lshlrev_b32_e32 v32, 16, v87
	v_mul_f32_e32 v15, v15, v33
	v_mul_f32_e32 v20, v20, v24
	v_mul_f32_e32 v21, v21, v25
	v_mul_f32_e32 v22, v22, v26
	v_mul_f32_e32 v23, v23, v27
	v_mul_f32_e32 v24, v12, v30
	v_mul_f32_e32 v25, v13, v31
	v_mul_f32_e32 v26, v14, v32
	v_cvt_pk_bf16_f32 v12, v20, v21
	v_cvt_pk_bf16_f32 v13, v22, v23
	v_cvt_pk_bf16_f32 v15, v26, v15
	v_cvt_pk_bf16_f32 v14, v24, v25
	global_store_dwordx4 v[28:29], v[12:15], off offset:256
	v_and_b32_e32 v21, 0xffff0000, v89
	v_and_b32_e32 v25, 0xffff0000, v91
	v_lshlrev_b64 v[12:13], 12, v[102:103]
	v_and_b32_e32 v15, 0xffff0000, v88
	v_lshlrev_b32_e32 v14, 16, v88
	v_lshlrev_b32_e32 v20, 16, v89
	v_lshlrev_b32_e32 v22, 16, v90
	v_and_b32_e32 v23, 0xffff0000, v90
	v_lshlrev_b32_e32 v24, 16, v91
	v_mul_f32_e32 v15, v17, v15
	v_mul_f32_e32 v17, v19, v21
	v_mul_f32_e32 v11, v11, v25
	v_lshl_add_u64 v[12:13], s[44:45], 0, v[12:13]
	v_mul_f32_e32 v14, v16, v14
	v_mul_f32_e32 v16, v18, v20
	v_mul_f32_e32 v18, v8, v22
	v_mul_f32_e32 v19, v9, v23
	v_mul_f32_e32 v20, v10, v24
	v_cvt_pk_bf16_f32 v8, v14, v15
	v_cvt_pk_bf16_f32 v9, v16, v17
	v_cvt_pk_bf16_f32 v10, v18, v19
	v_cvt_pk_bf16_f32 v11, v20, v11
	v_lshl_add_u64 v[12:13], v[12:13], 0, v[140:141]
	v_and_b32_e32 v17, 0xffff0000, v95
	global_store_dwordx4 v[12:13], v[8:11], off
	v_lshlrev_b32_e32 v14, 16, v94
	v_and_b32_e32 v15, 0xffff0000, v94
	v_lshlrev_b32_e32 v8, 16, v92
	v_and_b32_e32 v9, 0xffff0000, v92
	v_lshlrev_b32_e32 v10, 16, v93
	v_and_b32_e32 v11, 0xffff0000, v93
	v_lshlrev_b32_e32 v16, 16, v95
	v_mul_f32_e32 v3, v3, v17
	v_mul_f32_e32 v4, v4, v8
	v_mul_f32_e32 v5, v5, v9
	v_mul_f32_e32 v6, v6, v10
	v_mul_f32_e32 v7, v7, v11
	v_mul_f32_e32 v8, v0, v14
	v_mul_f32_e32 v9, v1, v15
	v_mul_f32_e32 v10, v2, v16
	v_cvt_pk_bf16_f32 v0, v4, v5
	v_cvt_pk_bf16_f32 v1, v6, v7
	v_cvt_pk_bf16_f32 v2, v8, v9
	v_cvt_pk_bf16_f32 v3, v10, v3
	global_store_dwordx4 v[12:13], v[0:3], off offset:256
	s_branch .LBB0_941
	s_waitcnt vmcnt(0)
	buffer_wbl2 sc1
	s_waitcnt vmcnt(0) lgkmcnt(0)
	s_waitcnt vmcnt(0)
	s_and_saveexec_b64 s[0:1], s[6:7]
	s_cbranch_execz .LBB0_940
	s_mov_b64 s[52:53], exec
	v_mbcnt_lo_u32_b32 v0, s52, 0
	v_mbcnt_hi_u32_b32 v0, s53, v0
	v_cmp_eq_u32_e32 vcc, 0, v0
	s_and_b64 s[42:43], exec, vcc
	s_mov_b64 exec, s[42:43]
	s_cbranch_execz .LBB0_940
	s_lshl_b32 s8, s70, 6
	s_lshl_b64 s[42:43], s[8:9], 2
	v_readlane_b32 s56, v255, 1
	v_readlane_b32 s57, v255, 2
	s_add_u32 s8, s56, s42
	s_addc_u32 s33, s57, s43
	s_add_u32 s42, s8, 0xfffc4e00
	s_addc_u32 s43, s33, -1
	s_bcnt1_i32_b64 s8, s[52:53]
	v_mov_b32_e32 v0, s8
	global_atomic_add v131, v0, s[42:43]
	s_branch .LBB0_940

; #define PG8_WAIT_V(n) asm volatile("s_waitcnt vmcnt(" #n ")" ::: "memory")
; #define PG8_BAR __builtin_amdgcn_s_barrier()
; template <class Epi, class S_t>
; __device__ __forceinline__ void gemm_phase(LAS unsigned char* lds, int lda, int ldb, const S_t& S, const Epi& E) {
;     ...
;         if (!has_next) break;
; #pragma unroll
;         for (int a = 0; a < 2; ++a)
; #pragma unroll
;             for (int b = 0; b < 2; ++b)
; #pragma unroll
;                 for (int m = 0; m < 4; ++m)
; #pragma unroll
;                     for (int n = 0; n < 2; ++n) acc[a][b][m][n] = (f32x4){0.f, 0.f, 0.f, 0.f};
;         cur = nxt; cA = nA; cB = nB; ++ui;
;     }
;     PG8_WAIT_V(0);
;     if (wr == 0) PG8_BAR;
;     PG8_BAR;
;     __device__ __forceinline__ void operator()(const f32x4 (&acc)[2][2][4][2], const Unit& u, int wr, int wc, int fr, int fq) const {
;     ...
;         if (!ADD && u.tag >= 1000) {
;             asm volatile("s_waitcnt vmcnt(0)" ::: "memory");
;             __builtin_amdgcn_fence(__ATOMIC_RELEASE, "agent");
;             asm volatile("s_waitcnt vmcnt(0)" ::: "memory");
;             if ((threadIdx.x & 63) == 0) __hip_atomic_fetch_add(flags + P7_FLAG(u.tag - 1000), 1u, __ATOMIC_RELAXED, __HIP_MEMORY_SCOPE_AGENT);
;         }
.LBB0_953:
	v_readfirstlane_b32 s98, v210
	s_lshr_b32 s98, s98, 3
	s_cmp_eq_u32 s98, s2
	s_cbranch_scc1 .Lp7x_done
	s_sub_i32 s99, s2, 32
	s_lshl_b32 s99, s99, 6
	s_addk_i32 s99, 0x1c00
	s_mov_b32 s2, s98
	s_cmp_lt_u32 s4, 64
	s_cbranch_scc0 .Lp7x_back
	buffer_wbl2 sc1
	s_waitcnt vmcnt(0)
	v_readlane_b32 s100, v255, 1
	v_readlane_b32 s101, v255, 2
	v_mov_b32_e32 v128, s99
	v_mov_b32_e32 v129, 8
	s_mov_b64 s[98:99], exec
	s_mov_b64 exec, 1
	s_nop 4
	global_atomic_add v128, v129, s[100:101]
	s_mov_b64 exec, s[98:99]
.Lp7x_back:
	s_add_u32 s46, s84, 0x19100000
	s_addc_u32 s47, s85, 0
	v_mov_b32_e32 v8, v212
	s_branch .Lp7x_entry
.Lp7x_done:
	s_cmp_lt_u32 s2, 32
	s_cbranch_scc0 .Lp7x_nopub
	s_cmp_lt_u32 s4, 64
	s_cbranch_scc0 .Lp7x_nopub
	buffer_wbl2 sc1
	s_waitcnt vmcnt(0)
	v_readlane_b32 s100, v255, 1
	v_readlane_b32 s101, v255, 2
	s_lshl_b32 s99, s2, 8
	s_addk_i32 s99, 0x3600
	v_mov_b32_e32 v128, s99
	v_mov_b32_e32 v129, 8
	s_mov_b64 s[98:99], exec
	s_mov_b64 exec, 1
	s_nop 4
	global_atomic_add v128, v129, s[100:101]
	s_mov_b64 exec, s[98:99]
